# EpiRes fast epilogue: the eight row-sum reductions are batched after the chunk loop (two LDS round trips instead of sixteen)
# baseline (speedup 1.0000x reference)
; DI float bflo(unsigned v) { return __uint_as_float(v << 16); }
; DI float bfhi(unsigned v) { return __uint_as_float(v & 0xffff0000u); }
; DI unsigned pk(float lo, float hi) { return pg8::cvt_pk_bf16(lo, hi); }
;     DI void operator()(const f32x4 (&acc)[2][2][4][2], const pg8::Unit& u, int wr, int wc, int fr, int fq) const {
;     ...
;             for (int m = 0; m < 4; ++m) {
;                 const int row = row0 + ai * 128 + m * 16;
;                 float sq = 0.f;
; #pragma unroll
;                 for (int bj = 0; bj < 2; ++bj) {
;                     const size_t off = (size_t)row * D + col0 + bj * 128;
;                     f32x4 a, b;
;                     if (mid) { a = *(const f32x4*)(Xin + off); b = *(const f32x4*)(Xin + off + 4); }
;                     else { const u32x4 h = *(const u32x4*)(XB + off); a = (f32x4){bflo(h.x), bfhi(h.x), bflo(h.y), bfhi(h.y)}; b = (f32x4){bflo(h.z), bfhi(h.z), bflo(h.w), bfhi(h.w)}; }
;                     a += acc[ai][bj][m][0] * scale; b += acc[ai][bj][m][1] * scale;
;                     if (X) { *(f32x4*)(X + off) = a; *(f32x4*)(X + off + 4) = b; }
;                     sq += (a[0] * a[0] + a[1] * a[1]) + (a[2] * a[2] + a[3] * a[3]) + (b[0] * b[0] + b[1] * b[1]) + (b[2] * b[2] + b[3] * b[3]);
;                     u32x4 w; w.x = pk(a[0], a[1]); w.y = pk(a[2], a[3]); w.z = pk(b[0], b[1]); w.w = pk(b[2], b[3]);
;                     *(u32x4*)(XB + off) = w;
;                 }
;                 sq += __shfl_xor(sq, 16); sq += __shfl_xor(sq, 32);
;                 if (fq == 0) ssq_out[(size_t)row * 16 + u.pn * 4 + wc] = sq;
.Lepi_nox_1:
	v_cvt_pk_bf16_f32 v174, v116, v117
	v_cvt_pk_bf16_f32 v175, v118, v119
	v_cvt_pk_bf16_f32 v176, v112, v113
	v_cvt_pk_bf16_f32 v177, v114, v115
	global_store_dwordx4 v153, v[174:177], s[72:73] offset:256
	v_mul_f32_e32 v150, v117, v117
	v_mul_f32_e32 v151, v119, v119
	v_fmac_f32_e32 v150, v116, v116
	v_fmac_f32_e32 v151, v118, v118
	v_add_f32_e32 v150, v150, v151
	v_mul_f32_e32 v151, v113, v113
	v_fmac_f32_e32 v151, v112, v112
	v_add_f32_e32 v150, v151, v150
	v_mul_f32_e32 v151, v115, v115
	v_fmac_f32_e32 v151, v114, v114
	v_add_f32_e32 v150, v151, v150
	v_add_f32_e32 v150, v247, v150
	v_mov_b32_e32 v124, v150
	v_add_u32_e32 v153, 0x8000, v152
	v_lshlrev_b32_e32 v149, 1, v153
	s_waitcnt vmcnt(15)
	v_lshlrev_b32_e32 v154, 16, v178
	v_and_b32_e32 v155, 0xffff0000, v178
	v_lshlrev_b32_e32 v164, 16, v179
	v_and_b32_e32 v165, 0xffff0000, v179
	v_lshlrev_b32_e32 v178, 16, v180
	v_and_b32_e32 v179, 0xffff0000, v180
	v_lshlrev_b32_e32 v180, 16, v181
	v_and_b32_e32 v181, 0xffff0000, v181
	v_pk_add_f32 v[108:109], v[108:109], v[154:155]
	v_pk_add_f32 v[110:111], v[110:111], v[164:165]
	v_pk_add_f32 v[104:105], v[104:105], v[178:179]
	v_pk_add_f32 v[106:107], v[106:107], v[180:181]
	s_and_b64 vcc, exec, s[76:77]
	s_cbranch_vccz .Lepi_nox_2
	global_store_dwordx4 v149, v[108:111], s[20:21] offset:0
	global_store_dwordx4 v149, v[104:107], s[20:21] offset:16
.Lepi_nox_2:
	v_cvt_pk_bf16_f32 v178, v108, v109
	v_cvt_pk_bf16_f32 v179, v110, v111
	v_cvt_pk_bf16_f32 v180, v104, v105
	v_cvt_pk_bf16_f32 v181, v106, v107
	global_store_dwordx4 v153, v[178:181], s[72:73]
	v_mul_f32_e32 v150, v109, v109
	v_fmac_f32_e32 v150, v108, v108
	v_mul_f32_e32 v151, v111, v111
	v_fmac_f32_e32 v151, v110, v110
	v_mul_f32_e32 v246, v105, v105
	v_add_f32_e32 v151, v150, v151
	v_fmac_f32_e32 v246, v104, v104
	v_add_f32_e32 v151, v246, v151
	v_mul_f32_e32 v246, v107, v107
	v_fmac_f32_e32 v246, v106, v106
	v_add_f32_e32 v247, v246, v151
	s_waitcnt vmcnt(15)
	v_lshlrev_b32_e32 v154, 16, v182
	v_and_b32_e32 v155, 0xffff0000, v182
	v_lshlrev_b32_e32 v164, 16, v183
	v_and_b32_e32 v165, 0xffff0000, v183
	v_lshlrev_b32_e32 v182, 16, v184
	v_and_b32_e32 v183, 0xffff0000, v184
	v_lshlrev_b32_e32 v184, 16, v185
	v_and_b32_e32 v185, 0xffff0000, v185
	v_pk_add_f32 v[100:101], v[100:101], v[154:155]
	v_pk_add_f32 v[102:103], v[102:103], v[164:165]
	v_pk_add_f32 v[96:97], v[96:97], v[182:183]
	v_pk_add_f32 v[98:99], v[98:99], v[184:185]
	s_and_b64 vcc, exec, s[76:77]
	s_cbranch_vccz .Lepi_nox_3
	global_store_dwordx4 v149, v[100:103], s[20:21] offset:512
	global_store_dwordx4 v149, v[96:99], s[20:21] offset:528
.Lepi_nox_3:
	v_cvt_pk_bf16_f32 v182, v100, v101
	v_cvt_pk_bf16_f32 v183, v102, v103
	v_cvt_pk_bf16_f32 v184, v96, v97
	v_cvt_pk_bf16_f32 v185, v98, v99
	global_store_dwordx4 v153, v[182:185], s[72:73] offset:256
	v_mul_f32_e32 v150, v101, v101
	v_mul_f32_e32 v151, v103, v103
	v_fmac_f32_e32 v150, v100, v100
	v_fmac_f32_e32 v151, v102, v102
	v_add_f32_e32 v150, v150, v151
	v_mul_f32_e32 v151, v97, v97
	v_fmac_f32_e32 v151, v96, v96
	v_add_f32_e32 v150, v151, v150
	v_mul_f32_e32 v151, v99, v99
	v_fmac_f32_e32 v151, v98, v98
	v_add_f32_e32 v150, v151, v150
	v_add_f32_e32 v150, v247, v150
	v_mov_b32_e32 v108, v150
	v_add_u32_e32 v153, 0x10000, v152
	v_lshlrev_b32_e32 v149, 1, v153
	s_waitcnt vmcnt(15)
	v_lshlrev_b32_e32 v154, 16, v186
	v_and_b32_e32 v155, 0xffff0000, v186
	v_lshlrev_b32_e32 v164, 16, v187
	v_and_b32_e32 v165, 0xffff0000, v187
	v_lshlrev_b32_e32 v186, 16, v188
	v_and_b32_e32 v187, 0xffff0000, v188
	v_lshlrev_b32_e32 v188, 16, v189
	v_and_b32_e32 v189, 0xffff0000, v189
	v_pk_add_f32 v[92:93], v[92:93], v[154:155]
	v_pk_add_f32 v[94:95], v[94:95], v[164:165]
	v_pk_add_f32 v[88:89], v[88:89], v[186:187]
	v_pk_add_f32 v[90:91], v[90:91], v[188:189]
	s_and_b64 vcc, exec, s[76:77]
	s_cbranch_vccz .Lepi_nox_4
	global_store_dwordx4 v149, v[92:95], s[20:21] offset:0
	global_store_dwordx4 v149, v[88:91], s[20:21] offset:16
.Lepi_nox_4:
	v_cvt_pk_bf16_f32 v186, v92, v93
	v_cvt_pk_bf16_f32 v187, v94, v95
	v_cvt_pk_bf16_f32 v188, v88, v89
	v_cvt_pk_bf16_f32 v189, v90, v91
	global_store_dwordx4 v153, v[186:189], s[72:73]
	v_mul_f32_e32 v150, v93, v93
	v_fmac_f32_e32 v150, v92, v92
	v_mul_f32_e32 v151, v95, v95
	v_fmac_f32_e32 v151, v94, v94
	v_mul_f32_e32 v246, v89, v89
	v_add_f32_e32 v151, v150, v151
	v_fmac_f32_e32 v246, v88, v88
	v_add_f32_e32 v151, v246, v151
	v_mul_f32_e32 v246, v91, v91
	v_fmac_f32_e32 v246, v90, v90
	v_add_f32_e32 v247, v246, v151
	s_waitcnt vmcnt(15)
	v_lshlrev_b32_e32 v154, 16, v190
	v_and_b32_e32 v155, 0xffff0000, v190
	v_lshlrev_b32_e32 v164, 16, v191
	v_and_b32_e32 v165, 0xffff0000, v191
	v_lshlrev_b32_e32 v190, 16, v192
	v_and_b32_e32 v191, 0xffff0000, v192
	v_lshlrev_b32_e32 v192, 16, v193
	v_and_b32_e32 v193, 0xffff0000, v193
	v_pk_add_f32 v[84:85], v[84:85], v[154:155]
	v_pk_add_f32 v[86:87], v[86:87], v[164:165]
	v_pk_add_f32 v[80:81], v[80:81], v[190:191]
	v_pk_add_f32 v[82:83], v[82:83], v[192:193]
	s_and_b64 vcc, exec, s[76:77]
	s_cbranch_vccz .Lepi_nox_5
	global_store_dwordx4 v149, v[84:87], s[20:21] offset:512
	global_store_dwordx4 v149, v[80:83], s[20:21] offset:528
; DI float bflo(unsigned v) { return __uint_as_float(v << 16); }
; DI float bfhi(unsigned v) { return __uint_as_float(v & 0xffff0000u); }
; DI unsigned pk(float lo, float hi) { return pg8::cvt_pk_bf16(lo, hi); }
;     DI void operator()(const f32x4 (&acc)[2][2][4][2], const pg8::Unit& u, int wr, int wc, int fr, int fq) const {
;     ...
;             for (int m = 0; m < 4; ++m) {
;                 const int row = row0 + ai * 128 + m * 16;
;                 float sq = 0.f;
; #pragma unroll
;                 for (int bj = 0; bj < 2; ++bj) {
;                     const size_t off = (size_t)row * D + col0 + bj * 128;
;                     f32x4 a, b;
;                     if (mid) { a = *(const f32x4*)(Xin + off); b = *(const f32x4*)(Xin + off + 4); }
;                     else { const u32x4 h = *(const u32x4*)(XB + off); a = (f32x4){bflo(h.x), bfhi(h.x), bflo(h.y), bfhi(h.y)}; b = (f32x4){bflo(h.z), bfhi(h.z), bflo(h.w), bfhi(h.w)}; }
;                     a += acc[ai][bj][m][0] * scale; b += acc[ai][bj][m][1] * scale;
;                     if (X) { *(f32x4*)(X + off) = a; *(f32x4*)(X + off + 4) = b; }
;                     sq += (a[0] * a[0] + a[1] * a[1]) + (a[2] * a[2] + a[3] * a[3]) + (b[0] * b[0] + b[1] * b[1]) + (b[2] * b[2] + b[3] * b[3]);
;                     u32x4 w; w.x = pk(a[0], a[1]); w.y = pk(a[2], a[3]); w.z = pk(b[0], b[1]); w.w = pk(b[2], b[3]);
;                     *(u32x4*)(XB + off) = w;
;                 }
;                 sq += __shfl_xor(sq, 16); sq += __shfl_xor(sq, 32);
;                 if (fq == 0) ssq_out[(size_t)row * 16 + u.pn * 4 + wc] = sq;
.Lepi_nox_5:
	v_cvt_pk_bf16_f32 v190, v84, v85
	v_cvt_pk_bf16_f32 v191, v86, v87
	v_cvt_pk_bf16_f32 v192, v80, v81
	v_cvt_pk_bf16_f32 v193, v82, v83
	global_store_dwordx4 v153, v[190:193], s[72:73] offset:256
	v_mul_f32_e32 v150, v85, v85
	v_mul_f32_e32 v151, v87, v87
	v_fmac_f32_e32 v150, v84, v84
	v_fmac_f32_e32 v151, v86, v86
	v_add_f32_e32 v150, v150, v151
	v_mul_f32_e32 v151, v81, v81
	v_fmac_f32_e32 v151, v80, v80
	v_add_f32_e32 v150, v151, v150
	v_mul_f32_e32 v151, v83, v83
	v_fmac_f32_e32 v151, v82, v82
	v_add_f32_e32 v150, v151, v150
	v_add_f32_e32 v150, v247, v150
	v_mov_b32_e32 v92, v150
	v_add_u32_e32 v153, 0x18000, v152
	v_lshlrev_b32_e32 v149, 1, v153
	s_waitcnt vmcnt(15)
	v_lshlrev_b32_e32 v154, 16, v214
	v_and_b32_e32 v155, 0xffff0000, v214
	v_lshlrev_b32_e32 v164, 16, v215
	v_and_b32_e32 v165, 0xffff0000, v215
	v_lshlrev_b32_e32 v214, 16, v216
	v_and_b32_e32 v215, 0xffff0000, v216
	v_lshlrev_b32_e32 v216, 16, v217
	v_and_b32_e32 v217, 0xffff0000, v217
	v_pk_add_f32 v[76:77], v[76:77], v[154:155]
	v_pk_add_f32 v[78:79], v[78:79], v[164:165]
	v_pk_add_f32 v[72:73], v[72:73], v[214:215]
	v_pk_add_f32 v[74:75], v[74:75], v[216:217]
	s_and_b64 vcc, exec, s[76:77]
	s_cbranch_vccz .Lepi_nox_6
	global_store_dwordx4 v149, v[76:79], s[20:21] offset:0
	global_store_dwordx4 v149, v[72:75], s[20:21] offset:16
.Lepi_nox_6:
	v_cvt_pk_bf16_f32 v214, v76, v77
	v_cvt_pk_bf16_f32 v215, v78, v79
	v_cvt_pk_bf16_f32 v216, v72, v73
	v_cvt_pk_bf16_f32 v217, v74, v75
	global_store_dwordx4 v153, v[214:217], s[72:73]
	v_mul_f32_e32 v150, v77, v77
	v_fmac_f32_e32 v150, v76, v76
	v_mul_f32_e32 v151, v79, v79
	v_fmac_f32_e32 v151, v78, v78
	v_mul_f32_e32 v246, v73, v73
	v_add_f32_e32 v151, v150, v151
	v_fmac_f32_e32 v246, v72, v72
	v_add_f32_e32 v151, v246, v151
	v_mul_f32_e32 v246, v75, v75
	v_fmac_f32_e32 v246, v74, v74
	v_add_f32_e32 v247, v246, v151
	s_waitcnt vmcnt(15)
	v_lshlrev_b32_e32 v154, 16, v218
	v_and_b32_e32 v155, 0xffff0000, v218
	v_lshlrev_b32_e32 v164, 16, v219
	v_and_b32_e32 v165, 0xffff0000, v219
	v_lshlrev_b32_e32 v218, 16, v220
	v_and_b32_e32 v219, 0xffff0000, v220
	v_lshlrev_b32_e32 v220, 16, v221
	v_and_b32_e32 v221, 0xffff0000, v221
	v_pk_add_f32 v[68:69], v[68:69], v[154:155]
	v_pk_add_f32 v[70:71], v[70:71], v[164:165]
	v_pk_add_f32 v[64:65], v[64:65], v[218:219]
	v_pk_add_f32 v[66:67], v[66:67], v[220:221]
	s_and_b64 vcc, exec, s[76:77]
	s_cbranch_vccz .Lepi_nox_7
	global_store_dwordx4 v149, v[68:71], s[20:21] offset:512
	global_store_dwordx4 v149, v[64:67], s[20:21] offset:528
.Lepi_nox_7:
	v_cvt_pk_bf16_f32 v218, v68, v69
	v_cvt_pk_bf16_f32 v219, v70, v71
	v_cvt_pk_bf16_f32 v220, v64, v65
	v_cvt_pk_bf16_f32 v221, v66, v67
	global_store_dwordx4 v153, v[218:221], s[72:73] offset:256
	v_mul_f32_e32 v150, v69, v69
	v_mul_f32_e32 v151, v71, v71
	v_fmac_f32_e32 v150, v68, v68
	v_fmac_f32_e32 v151, v70, v70
	v_add_f32_e32 v150, v150, v151
	v_mul_f32_e32 v151, v65, v65
	v_fmac_f32_e32 v151, v64, v64
	v_add_f32_e32 v150, v151, v150
	v_mul_f32_e32 v151, v67, v67
	v_fmac_f32_e32 v151, v66, v66
	v_add_f32_e32 v150, v151, v150
	v_add_f32_e32 v150, v247, v150
	v_mov_b32_e32 v76, v150
	v_add_u32_e32 v153, 0x40000, v152
	v_lshlrev_b32_e32 v149, 1, v153
	v_add_u32_e32 v148, 0x2000, v148
	s_waitcnt vmcnt(15)
	v_lshlrev_b32_e32 v154, 16, v222
	v_and_b32_e32 v155, 0xffff0000, v222
	v_lshlrev_b32_e32 v164, 16, v223
	v_and_b32_e32 v165, 0xffff0000, v223
	v_lshlrev_b32_e32 v222, 16, v224
	v_and_b32_e32 v223, 0xffff0000, v224
	v_lshlrev_b32_e32 v224, 16, v225
	v_and_b32_e32 v225, 0xffff0000, v225
	v_pk_add_f32 v[60:61], v[60:61], v[154:155]
	v_pk_add_f32 v[62:63], v[62:63], v[164:165]
	v_pk_add_f32 v[56:57], v[56:57], v[222:223]
	v_pk_add_f32 v[58:59], v[58:59], v[224:225]
	s_and_b64 vcc, exec, s[76:77]
	s_cbranch_vccz .Lepi_nox_8
	global_store_dwordx4 v149, v[60:63], s[20:21] offset:0
	global_store_dwordx4 v149, v[56:59], s[20:21] offset:16
.Lepi_nox_8:
	v_cvt_pk_bf16_f32 v222, v60, v61
	v_cvt_pk_bf16_f32 v223, v62, v63
	v_cvt_pk_bf16_f32 v224, v56, v57
	v_cvt_pk_bf16_f32 v225, v58, v59
	global_store_dwordx4 v153, v[222:225], s[72:73]
	v_mul_f32_e32 v150, v61, v61
	v_fmac_f32_e32 v150, v60, v60
	v_mul_f32_e32 v151, v63, v63
	v_fmac_f32_e32 v151, v62, v62
	v_mul_f32_e32 v246, v57, v57
	v_add_f32_e32 v151, v150, v151
	v_fmac_f32_e32 v246, v56, v56
	v_add_f32_e32 v151, v246, v151
	v_mul_f32_e32 v246, v59, v59
	v_fmac_f32_e32 v246, v58, v58
	v_add_f32_e32 v247, v246, v151
	s_waitcnt vmcnt(15)
	v_lshlrev_b32_e32 v154, 16, v226
	v_and_b32_e32 v155, 0xffff0000, v226
	v_lshlrev_b32_e32 v164, 16, v227
	v_and_b32_e32 v165, 0xffff0000, v227
	v_lshlrev_b32_e32 v226, 16, v228
	v_and_b32_e32 v227, 0xffff0000, v228
	v_lshlrev_b32_e32 v228, 16, v229
	v_and_b32_e32 v229, 0xffff0000, v229
	v_pk_add_f32 v[52:53], v[52:53], v[154:155]
	v_pk_add_f32 v[54:55], v[54:55], v[164:165]
	v_pk_add_f32 v[48:49], v[48:49], v[226:227]
	v_pk_add_f32 v[50:51], v[50:51], v[228:229]
	s_and_b64 vcc, exec, s[76:77]
	s_cbranch_vccz .Lepi_nox_9
	global_store_dwordx4 v149, v[52:55], s[20:21] offset:512
	global_store_dwordx4 v149, v[48:51], s[20:21] offset:528
; DI float bflo(unsigned v) { return __uint_as_float(v << 16); }
; DI float bfhi(unsigned v) { return __uint_as_float(v & 0xffff0000u); }
; DI unsigned pk(float lo, float hi) { return pg8::cvt_pk_bf16(lo, hi); }
;     DI void operator()(const f32x4 (&acc)[2][2][4][2], const pg8::Unit& u, int wr, int wc, int fr, int fq) const {
;     ...
;             for (int m = 0; m < 4; ++m) {
;                 const int row = row0 + ai * 128 + m * 16;
;                 float sq = 0.f;
; #pragma unroll
;                 for (int bj = 0; bj < 2; ++bj) {
;                     const size_t off = (size_t)row * D + col0 + bj * 128;
;                     f32x4 a, b;
;                     if (mid) { a = *(const f32x4*)(Xin + off); b = *(const f32x4*)(Xin + off + 4); }
;                     else { const u32x4 h = *(const u32x4*)(XB + off); a = (f32x4){bflo(h.x), bfhi(h.x), bflo(h.y), bfhi(h.y)}; b = (f32x4){bflo(h.z), bfhi(h.z), bflo(h.w), bfhi(h.w)}; }
;                     a += acc[ai][bj][m][0] * scale; b += acc[ai][bj][m][1] * scale;
;                     if (X) { *(f32x4*)(X + off) = a; *(f32x4*)(X + off + 4) = b; }
;                     sq += (a[0] * a[0] + a[1] * a[1]) + (a[2] * a[2] + a[3] * a[3]) + (b[0] * b[0] + b[1] * b[1]) + (b[2] * b[2] + b[3] * b[3]);
;                     u32x4 w; w.x = pk(a[0], a[1]); w.y = pk(a[2], a[3]); w.z = pk(b[0], b[1]); w.w = pk(b[2], b[3]);
;                     *(u32x4*)(XB + off) = w;
;                 }
;                 sq += __shfl_xor(sq, 16); sq += __shfl_xor(sq, 32);
;                 if (fq == 0) ssq_out[(size_t)row * 16 + u.pn * 4 + wc] = sq;
.Lepi_nox_9:
	v_cvt_pk_bf16_f32 v226, v52, v53
	v_cvt_pk_bf16_f32 v227, v54, v55
	v_cvt_pk_bf16_f32 v228, v48, v49
	v_cvt_pk_bf16_f32 v229, v50, v51
	global_store_dwordx4 v153, v[226:229], s[72:73] offset:256
	v_mul_f32_e32 v150, v53, v53
	v_mul_f32_e32 v151, v55, v55
	v_fmac_f32_e32 v150, v52, v52
	v_fmac_f32_e32 v151, v54, v54
	v_add_f32_e32 v150, v150, v151
	v_mul_f32_e32 v151, v49, v49
	v_fmac_f32_e32 v151, v48, v48
	v_add_f32_e32 v150, v151, v150
	v_mul_f32_e32 v151, v51, v51
	v_fmac_f32_e32 v151, v50, v50
	v_add_f32_e32 v150, v151, v150
	v_add_f32_e32 v150, v247, v150
	v_mov_b32_e32 v60, v150
	v_add_u32_e32 v153, 0x48000, v152
	v_lshlrev_b32_e32 v149, 1, v153
	s_waitcnt vmcnt(15)
	v_lshlrev_b32_e32 v154, 16, v230
	v_and_b32_e32 v155, 0xffff0000, v230
	v_lshlrev_b32_e32 v164, 16, v231
	v_and_b32_e32 v165, 0xffff0000, v231
	v_lshlrev_b32_e32 v230, 16, v232
	v_and_b32_e32 v231, 0xffff0000, v232
	v_lshlrev_b32_e32 v232, 16, v233
	v_and_b32_e32 v233, 0xffff0000, v233
	v_pk_add_f32 v[44:45], v[44:45], v[154:155]
	v_pk_add_f32 v[46:47], v[46:47], v[164:165]
	v_pk_add_f32 v[40:41], v[40:41], v[230:231]
	v_pk_add_f32 v[42:43], v[42:43], v[232:233]
	s_and_b64 vcc, exec, s[76:77]
	s_cbranch_vccz .Lepi_nox_10
	global_store_dwordx4 v149, v[44:47], s[20:21] offset:0
	global_store_dwordx4 v149, v[40:43], s[20:21] offset:16
.Lepi_nox_10:
	v_cvt_pk_bf16_f32 v230, v44, v45
	v_cvt_pk_bf16_f32 v231, v46, v47
	v_cvt_pk_bf16_f32 v232, v40, v41
	v_cvt_pk_bf16_f32 v233, v42, v43
	global_store_dwordx4 v153, v[230:233], s[72:73]
	v_mul_f32_e32 v150, v45, v45
	v_fmac_f32_e32 v150, v44, v44
	v_mul_f32_e32 v151, v47, v47
	v_fmac_f32_e32 v151, v46, v46
	v_mul_f32_e32 v246, v41, v41
	v_add_f32_e32 v151, v150, v151
	v_fmac_f32_e32 v246, v40, v40
	v_add_f32_e32 v151, v246, v151
	v_mul_f32_e32 v246, v43, v43
	v_fmac_f32_e32 v246, v42, v42
	v_add_f32_e32 v247, v246, v151
	s_waitcnt vmcnt(15)
	v_lshlrev_b32_e32 v154, 16, v234
	v_and_b32_e32 v155, 0xffff0000, v234
	v_lshlrev_b32_e32 v164, 16, v235
	v_and_b32_e32 v165, 0xffff0000, v235
	v_lshlrev_b32_e32 v234, 16, v236
	v_and_b32_e32 v235, 0xffff0000, v236
	v_lshlrev_b32_e32 v236, 16, v237
	v_and_b32_e32 v237, 0xffff0000, v237
	v_pk_add_f32 v[36:37], v[36:37], v[154:155]
	v_pk_add_f32 v[38:39], v[38:39], v[164:165]
	v_pk_add_f32 v[32:33], v[32:33], v[234:235]
	v_pk_add_f32 v[34:35], v[34:35], v[236:237]
	s_and_b64 vcc, exec, s[76:77]
	s_cbranch_vccz .Lepi_nox_11
	global_store_dwordx4 v149, v[36:39], s[20:21] offset:512
	global_store_dwordx4 v149, v[32:35], s[20:21] offset:528
.Lepi_nox_11:
	v_cvt_pk_bf16_f32 v234, v36, v37
	v_cvt_pk_bf16_f32 v235, v38, v39
	v_cvt_pk_bf16_f32 v236, v32, v33
	v_cvt_pk_bf16_f32 v237, v34, v35
	global_store_dwordx4 v153, v[234:237], s[72:73] offset:256
	v_mul_f32_e32 v150, v37, v37
	v_mul_f32_e32 v151, v39, v39
	v_fmac_f32_e32 v150, v36, v36
	v_fmac_f32_e32 v151, v38, v38
	v_add_f32_e32 v150, v150, v151
	v_mul_f32_e32 v151, v33, v33
	v_fmac_f32_e32 v151, v32, v32
	v_add_f32_e32 v150, v151, v150
	v_mul_f32_e32 v151, v35, v35
	v_fmac_f32_e32 v151, v34, v34
	v_add_f32_e32 v150, v151, v150
	v_add_f32_e32 v150, v247, v150
	v_mov_b32_e32 v44, v150
	v_add_u32_e32 v153, 0x50000, v152
	v_lshlrev_b32_e32 v149, 1, v153
	s_waitcnt vmcnt(15)
	v_lshlrev_b32_e32 v154, 16, v238
	v_and_b32_e32 v155, 0xffff0000, v238
	v_lshlrev_b32_e32 v164, 16, v239
	v_and_b32_e32 v165, 0xffff0000, v239
	v_lshlrev_b32_e32 v238, 16, v240
	v_and_b32_e32 v239, 0xffff0000, v240
	v_lshlrev_b32_e32 v240, 16, v241
	v_and_b32_e32 v241, 0xffff0000, v241
	v_pk_add_f32 v[28:29], v[28:29], v[154:155]
	v_pk_add_f32 v[30:31], v[30:31], v[164:165]
	v_pk_add_f32 v[24:25], v[24:25], v[238:239]
	v_pk_add_f32 v[26:27], v[26:27], v[240:241]
	s_and_b64 vcc, exec, s[76:77]
	s_cbranch_vccz .Lepi_nox_12
	global_store_dwordx4 v149, v[28:31], s[20:21] offset:0
	global_store_dwordx4 v149, v[24:27], s[20:21] offset:16
.Lepi_nox_12:
	v_cvt_pk_bf16_f32 v238, v28, v29
	v_cvt_pk_bf16_f32 v239, v30, v31
	v_cvt_pk_bf16_f32 v240, v24, v25
	v_cvt_pk_bf16_f32 v241, v26, v27
	global_store_dwordx4 v153, v[238:241], s[72:73]
	v_mul_f32_e32 v150, v29, v29
	v_fmac_f32_e32 v150, v28, v28
	v_mul_f32_e32 v151, v31, v31
	v_fmac_f32_e32 v151, v30, v30
	v_mul_f32_e32 v246, v25, v25
	v_add_f32_e32 v151, v150, v151
	v_fmac_f32_e32 v246, v24, v24
	v_add_f32_e32 v151, v246, v151
	v_mul_f32_e32 v246, v27, v27
	v_fmac_f32_e32 v246, v26, v26
	v_add_f32_e32 v247, v246, v151
	s_waitcnt vmcnt(15)
	v_lshlrev_b32_e32 v154, 16, v242
	v_and_b32_e32 v155, 0xffff0000, v242
	v_lshlrev_b32_e32 v164, 16, v243
	v_and_b32_e32 v165, 0xffff0000, v243
	v_lshlrev_b32_e32 v242, 16, v244
	v_and_b32_e32 v243, 0xffff0000, v244
	v_lshlrev_b32_e32 v244, 16, v245
	v_and_b32_e32 v245, 0xffff0000, v245
	v_pk_add_f32 v[20:21], v[20:21], v[154:155]
	v_pk_add_f32 v[22:23], v[22:23], v[164:165]
	v_pk_add_f32 v[16:17], v[16:17], v[242:243]
	v_pk_add_f32 v[18:19], v[18:19], v[244:245]
	s_and_b64 vcc, exec, s[76:77]
	s_cbranch_vccz .Lepi_nox_13
	global_store_dwordx4 v149, v[20:23], s[20:21] offset:512
	global_store_dwordx4 v149, v[16:19], s[20:21] offset:528
; DI float bflo(unsigned v) { return __uint_as_float(v << 16); }
; DI float bfhi(unsigned v) { return __uint_as_float(v & 0xffff0000u); }
; DI unsigned pk(float lo, float hi) { return pg8::cvt_pk_bf16(lo, hi); }
;     DI void operator()(const f32x4 (&acc)[2][2][4][2], const pg8::Unit& u, int wr, int wc, int fr, int fq) const {
;     ...
;                 for (int bj = 0; bj < 2; ++bj) {
;                     const size_t off = (size_t)row * D + col0 + bj * 128;
;                     f32x4 a, b;
;                     if (mid) { a = *(const f32x4*)(Xin + off); b = *(const f32x4*)(Xin + off + 4); }
;                     else { const u32x4 h = *(const u32x4*)(XB + off); a = (f32x4){bflo(h.x), bfhi(h.x), bflo(h.y), bfhi(h.y)}; b = (f32x4){bflo(h.z), bfhi(h.z), bflo(h.w), bfhi(h.w)}; }
;                     a += acc[ai][bj][m][0] * scale; b += acc[ai][bj][m][1] * scale;
;                     if (X) { *(f32x4*)(X + off) = a; *(f32x4*)(X + off + 4) = b; }
;                     sq += (a[0] * a[0] + a[1] * a[1]) + (a[2] * a[2] + a[3] * a[3]) + (b[0] * b[0] + b[1] * b[1]) + (b[2] * b[2] + b[3] * b[3]);
;                     u32x4 w; w.x = pk(a[0], a[1]); w.y = pk(a[2], a[3]); w.z = pk(b[0], b[1]); w.w = pk(b[2], b[3]);
;                     *(u32x4*)(XB + off) = w;
;                 }
;                 sq += __shfl_xor(sq, 16); sq += __shfl_xor(sq, 32);
;                 if (fq == 0) ssq_out[(size_t)row * 16 + u.pn * 4 + wc] = sq;
;             }
.Lepi_nox_13:
	v_cvt_pk_bf16_f32 v242, v20, v21
	v_cvt_pk_bf16_f32 v243, v22, v23
	v_cvt_pk_bf16_f32 v244, v16, v17
	v_cvt_pk_bf16_f32 v245, v18, v19
	global_store_dwordx4 v153, v[242:245], s[72:73] offset:256
	v_mul_f32_e32 v150, v21, v21
	v_mul_f32_e32 v151, v23, v23
	v_fmac_f32_e32 v150, v20, v20
	v_fmac_f32_e32 v151, v22, v22
	v_add_f32_e32 v150, v150, v151
	v_mul_f32_e32 v151, v17, v17
	v_fmac_f32_e32 v151, v16, v16
	v_add_f32_e32 v150, v151, v150
	v_mul_f32_e32 v151, v19, v19
	v_fmac_f32_e32 v151, v18, v18
	v_add_f32_e32 v150, v151, v150
	v_add_f32_e32 v150, v247, v150
	v_mov_b32_e32 v28, v150
	v_add_u32_e32 v153, 0x58000, v152
	v_lshlrev_b32_e32 v149, 1, v153
	s_waitcnt vmcnt(15)
	v_lshlrev_b32_e32 v154, 16, v128
	v_and_b32_e32 v155, 0xffff0000, v128
	v_lshlrev_b32_e32 v164, 16, v129
	v_and_b32_e32 v165, 0xffff0000, v129
	v_lshlrev_b32_e32 v128, 16, v130
	v_and_b32_e32 v129, 0xffff0000, v130
	v_lshlrev_b32_e32 v130, 16, v131
	v_and_b32_e32 v131, 0xffff0000, v131
	v_pk_add_f32 v[12:13], v[12:13], v[154:155]
	v_pk_add_f32 v[14:15], v[14:15], v[164:165]
	v_pk_add_f32 v[8:9], v[8:9], v[128:129]
	v_pk_add_f32 v[10:11], v[10:11], v[130:131]
	s_and_b64 vcc, exec, s[76:77]
	s_cbranch_vccz .Lepi_nox_14
	global_store_dwordx4 v149, v[12:15], s[20:21] offset:0
	global_store_dwordx4 v149, v[8:11], s[20:21] offset:16
.Lepi_nox_14:
	v_cvt_pk_bf16_f32 v128, v12, v13
	v_cvt_pk_bf16_f32 v129, v14, v15
	v_cvt_pk_bf16_f32 v130, v8, v9
	v_cvt_pk_bf16_f32 v131, v10, v11
	global_store_dwordx4 v153, v[128:131], s[72:73]
	v_mul_f32_e32 v150, v13, v13
	v_fmac_f32_e32 v150, v12, v12
	v_mul_f32_e32 v151, v15, v15
	v_fmac_f32_e32 v151, v14, v14
	v_mul_f32_e32 v246, v9, v9
	v_add_f32_e32 v151, v150, v151
	v_fmac_f32_e32 v246, v8, v8
	v_add_f32_e32 v151, v246, v151
	v_mul_f32_e32 v246, v11, v11
	v_fmac_f32_e32 v246, v10, v10
	v_add_f32_e32 v247, v246, v151
	s_waitcnt vmcnt(15)
	v_lshlrev_b32_e32 v154, 16, v132
	v_and_b32_e32 v155, 0xffff0000, v132
	v_lshlrev_b32_e32 v164, 16, v133
	v_and_b32_e32 v165, 0xffff0000, v133
	v_lshlrev_b32_e32 v132, 16, v134
	v_and_b32_e32 v133, 0xffff0000, v134
	v_lshlrev_b32_e32 v134, 16, v135
	v_and_b32_e32 v135, 0xffff0000, v135
	v_pk_add_f32 v[4:5], v[4:5], v[154:155]
	v_pk_add_f32 v[6:7], v[6:7], v[164:165]
	v_pk_add_f32 v[0:1], v[0:1], v[132:133]
	v_pk_add_f32 v[2:3], v[2:3], v[134:135]
	s_and_b64 vcc, exec, s[76:77]
	s_cbranch_vccz .Lepi_nox_15
	global_store_dwordx4 v149, v[4:7], s[20:21] offset:512
	global_store_dwordx4 v149, v[0:3], s[20:21] offset:528
.Lepi_nox_15:
	v_cvt_pk_bf16_f32 v132, v4, v5
	v_cvt_pk_bf16_f32 v133, v6, v7
	v_cvt_pk_bf16_f32 v134, v0, v1
	v_cvt_pk_bf16_f32 v135, v2, v3
	global_store_dwordx4 v153, v[132:135], s[72:73] offset:256
	v_mul_f32_e32 v150, v5, v5
	v_mul_f32_e32 v151, v7, v7
	v_fmac_f32_e32 v150, v4, v4
	v_fmac_f32_e32 v151, v6, v6
	v_add_f32_e32 v150, v150, v151
	v_mul_f32_e32 v151, v1, v1
	v_fmac_f32_e32 v151, v0, v0
	v_add_f32_e32 v150, v151, v150
	v_mul_f32_e32 v151, v3, v3
	v_fmac_f32_e32 v151, v2, v2
	v_add_f32_e32 v150, v151, v150
	v_add_f32_e32 v150, v247, v150
	v_mov_b32_e32 v12, v150
	ds_bpermute_b32 v120, v194, v124
	ds_bpermute_b32 v104, v194, v108
	ds_bpermute_b32 v88, v194, v92
	ds_bpermute_b32 v72, v194, v76
	ds_bpermute_b32 v56, v194, v60
	ds_bpermute_b32 v40, v194, v44
	ds_bpermute_b32 v24, v194, v28
	ds_bpermute_b32 v8, v194, v12
	s_waitcnt lgkmcnt(0)
	v_add_f32_e32 v124, v124, v120
	v_add_f32_e32 v108, v108, v104
	v_add_f32_e32 v92, v92, v88
	v_add_f32_e32 v76, v76, v72
	v_add_f32_e32 v60, v60, v56
	v_add_f32_e32 v44, v44, v40
	v_add_f32_e32 v28, v28, v24
	v_add_f32_e32 v12, v12, v8
	ds_bpermute_b32 v120, v195, v124
	ds_bpermute_b32 v104, v195, v108
	ds_bpermute_b32 v88, v195, v92
	ds_bpermute_b32 v72, v195, v76
	ds_bpermute_b32 v56, v195, v60
	ds_bpermute_b32 v40, v195, v44
	ds_bpermute_b32 v24, v195, v28
	ds_bpermute_b32 v8, v195, v12
	s_waitcnt lgkmcnt(0)
	v_add_f32_e32 v124, v124, v120
	v_add_f32_e32 v108, v108, v104
	v_add_f32_e32 v92, v92, v88
	v_add_f32_e32 v76, v76, v72
	v_add_f32_e32 v60, v60, v56
	v_add_f32_e32 v44, v44, v40
	v_add_f32_e32 v28, v28, v24
	v_add_f32_e32 v12, v12, v8
	s_and_saveexec_b64 s[82:83], s[36:37]
	v_add_u32_e32 v148, 0xffffe000, v148
	global_store_dword v148, v124, s[24:25] offset:0
	global_store_dword v148, v108, s[24:25] offset:1024
	global_store_dword v148, v92, s[24:25] offset:2048
	global_store_dword v148, v76, s[24:25] offset:3072
	v_add_u32_e32 v148, 0x2000, v148
	global_store_dword v148, v60, s[24:25] offset:0
	global_store_dword v148, v44, s[24:25] offset:1024
	global_store_dword v148, v28, s[24:25] offset:2048
	global_store_dword v148, v12, s[24:25] offset:3072
	s_or_b64 exec, exec, s[82:83]
	s_branch .Lepi_done
